# P5 final tile stores write-through (sc1) so the barrier's L2 write-back finds less dirty data
# baseline (speedup 1.0000x reference)
mk_p5_chk:
	s_cmp_lg_u64 s[40:41], 0
	s_cbranch_scc1 .LBB0_716
	s_lshl_b32 s98, s74, 8
	s_add_i32 s98, s98, s48
	s_lshl_b32 s98, s98, 14
	s_lshl_b32 s99, s75, 8
	s_or_b32 s99, s99, s50
	s_lshl_b32 s99, s99, 1
	s_add_u32 s98, s98, s99
	s_add_u32 s98, s76, s98
	s_addc_u32 s99, s77, 0
	s_add_u32 s100, s98, 0x200000
	s_addc_u32 s101, s99, 0
	s_add_u32 s80, s46, 0x100
	s_addc_u32 s81, s47, 0
	s_cmp_eq_u32 s89, 28
	s_cselect_b32 s28, vcc_lo, s80
	s_cselect_b32 s29, s37, s81
	s_cselect_b32 s23, s21, s88
	s_cselect_b32 s22, s86, s87
	s_add_u32 s26, s28, 0x80
	s_addc_u32 s27, s29, 0
	s_add_u32 s66, s22, 0x80
	s_addc_u32 s67, s23, 0
	s_add_u32 s90, s46, 0x80080
	s_addc_u32 s91, s47, 0
	s_add_u32 s52, s28, 0x80000
	s_addc_u32 s53, s29, 0
	s_add_u32 s56, s22, 0x80000
	s_addc_u32 s57, s23, 0
	s_add_u32 s46, s22, 0x80080
	s_addc_u32 s47, s23, 0
	s_add_i32 s92, 0, 0x10000
	v_add_u32_e32 v133, s92, v129
	s_add_i32 s93, 0, 0x14000
	ds_read_b128 v[134:137], v133
	ds_read_b128 v[138:141], v133 offset:1024
	ds_read_b128 v[142:145], v133 offset:2048
	ds_read_b128 v[146:149], v133 offset:3072
	v_add_u32_e32 v133, s93, v129
	ds_read_b128 v[150:153], v133
	ds_read_b128 v[154:157], v133 offset:1024
	ds_read_b128 v[158:161], v133 offset:2048
	ds_read_b128 v[162:165], v133 offset:3072
	s_add_i32 m0, s0, 0xc000
	ds_read_b128 v[166:169], v131
	ds_read_b128 v[170:173], v131 offset:1024
	ds_read_b128 v[174:177], v131 offset:2048
	ds_read_b128 v[178:181], v131 offset:3072
	ds_read_b128 v[182:185], v131 offset:4096
	ds_read_b128 v[186:189], v131 offset:5120
	ds_read_b128 v[202:205], v131 offset:6144
	ds_read_b128 v[206:209], v131 offset:7168
	global_load_lds_dwordx4 v128, s[90:91]
	s_add_i32 m0, s0, 0xe000
	s_nop 0
	global_load_lds_dwordx4 v130, s[90:91]
	s_waitcnt vmcnt(8)
	s_waitcnt lgkmcnt(0)
	s_barrier
	s_setprio 1
	s_waitcnt lgkmcnt(0)
	v_mfma_f32_16x16x32_bf16 v[124:127], v[134:137], v[166:169], v[124:127]
	v_mfma_f32_16x16x32_bf16 v[120:123], v[142:145], v[166:169], v[120:123]
	v_mfma_f32_16x16x32_bf16 v[108:111], v[134:137], v[174:177], v[108:111]
	v_mfma_f32_16x16x32_bf16 v[104:107], v[142:145], v[174:177], v[104:107]
	v_mfma_f32_16x16x32_bf16 v[92:95], v[134:137], v[182:185], v[92:95]
	v_mfma_f32_16x16x32_bf16 v[88:91], v[142:145], v[182:185], v[88:91]
	v_mfma_f32_16x16x32_bf16 v[76:79], v[134:137], v[202:205], v[76:79]
	v_mfma_f32_16x16x32_bf16 v[72:75], v[142:145], v[202:205], v[72:75]
	v_mfma_f32_16x16x32_bf16 v[124:127], v[138:141], v[170:173], v[124:127]
	v_mfma_f32_16x16x32_bf16 v[120:123], v[146:149], v[170:173], v[120:123]
	v_mfma_f32_16x16x32_bf16 v[108:111], v[138:141], v[178:181], v[108:111]
	v_mfma_f32_16x16x32_bf16 v[104:107], v[146:149], v[178:181], v[104:107]
	v_mfma_f32_16x16x32_bf16 v[92:95], v[138:141], v[186:189], v[92:95]
	v_mfma_f32_16x16x32_bf16 v[88:91], v[146:149], v[186:189], v[88:91]
	v_mfma_f32_16x16x32_bf16 v[76:79], v[138:141], v[206:209], v[76:79]
	v_mfma_f32_16x16x32_bf16 v[72:75], v[146:149], v[206:209], v[72:75]
	s_setprio 0
	s_setprio 1
	v_mfma_f32_16x16x32_bf16 v[116:119], v[150:153], v[166:169], v[116:119]
	v_mfma_f32_16x16x32_bf16 v[112:115], v[158:161], v[166:169], v[112:115]
	v_mfma_f32_16x16x32_bf16 v[100:103], v[150:153], v[174:177], v[100:103]
	v_mfma_f32_16x16x32_bf16 v[96:99], v[158:161], v[174:177], v[96:99]
	v_mfma_f32_16x16x32_bf16 v[84:87], v[150:153], v[182:185], v[84:87]
	v_mfma_f32_16x16x32_bf16 v[80:83], v[158:161], v[182:185], v[80:83]
	v_mfma_f32_16x16x32_bf16 v[68:71], v[150:153], v[202:205], v[68:71]
	v_mfma_f32_16x16x32_bf16 v[64:67], v[158:161], v[202:205], v[64:67]
	v_mfma_f32_16x16x32_bf16 v[116:119], v[154:157], v[170:173], v[116:119]
	v_mfma_f32_16x16x32_bf16 v[112:115], v[162:165], v[170:173], v[112:115]
	v_mfma_f32_16x16x32_bf16 v[100:103], v[154:157], v[178:181], v[100:103]
	v_mfma_f32_16x16x32_bf16 v[96:99], v[162:165], v[178:181], v[96:99]
	v_mfma_f32_16x16x32_bf16 v[84:87], v[154:157], v[186:189], v[84:87]
	v_mfma_f32_16x16x32_bf16 v[80:83], v[162:165], v[186:189], v[80:83]
	v_mfma_f32_16x16x32_bf16 v[68:71], v[154:157], v[206:209], v[68:71]
	v_mfma_f32_16x16x32_bf16 v[64:67], v[162:165], v[206:209], v[64:67]
	s_setprio 0
	s_barrier
	s_add_i32 s90, s92, s33
	s_mov_b32 m0, s90
	ds_read_b128 v[166:169], v131 offset:16384
	ds_read_b128 v[170:173], v131 offset:17408
	ds_read_b128 v[174:177], v131 offset:18432
	ds_read_b128 v[178:181], v131 offset:19456
	ds_read_b128 v[182:185], v131 offset:20480
	ds_read_b128 v[186:189], v131 offset:21504
	ds_read_b128 v[202:205], v131 offset:22528
	ds_read_b128 v[206:209], v131 offset:23552
	global_load_lds_dwordx4 v192, s[22:23]
	s_add_i32 m0, s90, 0x2000
	s_nop 0
	global_load_lds_dwordx4 v132, s[22:23]
	s_add_i32 s22, s93, s33
	s_mov_b32 m0, s22
	s_nop 0
	global_load_lds_dwordx4 v192, s[56:57]
	s_add_i32 m0, s22, 0x2000
	s_nop 0
	global_load_lds_dwordx4 v132, s[56:57]
	s_mov_b32 m0, s0
	s_nop 0
	global_load_lds_dwordx4 v128, s[28:29]
	s_mov_b32 m0, s1
	s_nop 0
	global_load_lds_dwordx4 v130, s[28:29]
	s_waitcnt vmcnt(8)
	s_waitcnt lgkmcnt(0)
	s_barrier
	s_setprio 1
	s_waitcnt lgkmcnt(0)
	v_mfma_f32_16x16x32_bf16 v[60:63], v[134:137], v[166:169], v[60:63]
	v_mfma_f32_16x16x32_bf16 v[56:59], v[142:145], v[166:169], v[56:59]
	v_mfma_f32_16x16x32_bf16 v[44:47], v[134:137], v[174:177], v[44:47]
	v_mfma_f32_16x16x32_bf16 v[40:43], v[142:145], v[174:177], v[40:43]
	v_mfma_f32_16x16x32_bf16 v[28:31], v[134:137], v[182:185], v[28:31]
	v_mfma_f32_16x16x32_bf16 v[24:27], v[142:145], v[182:185], v[24:27]
	v_mfma_f32_16x16x32_bf16 v[12:15], v[134:137], v[202:205], v[12:15]
	v_mfma_f32_16x16x32_bf16 v[8:11], v[142:145], v[202:205], v[8:11]
	v_mfma_f32_16x16x32_bf16 v[60:63], v[138:141], v[170:173], v[60:63]
	v_mfma_f32_16x16x32_bf16 v[56:59], v[146:149], v[170:173], v[56:59]
	v_mfma_f32_16x16x32_bf16 v[44:47], v[138:141], v[178:181], v[44:47]
	v_mfma_f32_16x16x32_bf16 v[40:43], v[146:149], v[178:181], v[40:43]
	v_mfma_f32_16x16x32_bf16 v[28:31], v[138:141], v[186:189], v[28:31]
	v_mfma_f32_16x16x32_bf16 v[24:27], v[146:149], v[186:189], v[24:27]
	v_mfma_f32_16x16x32_bf16 v[12:15], v[138:141], v[206:209], v[12:15]
	v_mfma_f32_16x16x32_bf16 v[8:11], v[146:149], v[206:209], v[8:11]
	s_setprio 0
	s_setprio 1
	v_mfma_f32_16x16x32_bf16 v[52:55], v[150:153], v[166:169], v[52:55]
	v_mfma_f32_16x16x32_bf16 v[48:51], v[158:161], v[166:169], v[48:51]
	v_mfma_f32_16x16x32_bf16 v[36:39], v[150:153], v[174:177], v[36:39]
	v_mfma_f32_16x16x32_bf16 v[32:35], v[158:161], v[174:177], v[32:35]
	v_mfma_f32_16x16x32_bf16 v[20:23], v[150:153], v[182:185], v[20:23]
	v_mfma_f32_16x16x32_bf16 v[16:19], v[158:161], v[182:185], v[16:19]
	v_mfma_f32_16x16x32_bf16 v[4:7], v[150:153], v[202:205], v[4:7]
	v_mfma_f32_16x16x32_bf16 v[0:3], v[158:161], v[202:205], v[0:3]
	v_mfma_f32_16x16x32_bf16 v[52:55], v[154:157], v[170:173], v[52:55]
	v_mfma_f32_16x16x32_bf16 v[48:51], v[162:165], v[170:173], v[48:51]
	v_mfma_f32_16x16x32_bf16 v[36:39], v[154:157], v[178:181], v[36:39]
	v_mfma_f32_16x16x32_bf16 v[32:35], v[162:165], v[178:181], v[32:35]
	v_mfma_f32_16x16x32_bf16 v[20:23], v[154:157], v[186:189], v[20:23]
	v_mfma_f32_16x16x32_bf16 v[16:19], v[162:165], v[186:189], v[16:19]
	v_mfma_f32_16x16x32_bf16 v[4:7], v[154:157], v[206:209], v[4:7]
	v_mfma_f32_16x16x32_bf16 v[0:3], v[162:165], v[206:209], v[0:3]
	s_setprio 0
	s_barrier
	s_add_i32 s22, 0, 0x18000
	v_add_u32_e32 v133, s22, v129
	s_add_i32 s23, 0, 0x1c000
	ds_read_b128 v[134:137], v133
	ds_read_b128 v[138:141], v133 offset:1024
	ds_read_b128 v[142:145], v133 offset:2048
	ds_read_b128 v[146:149], v133 offset:3072
	v_add_u32_e32 v133, s23, v129
	ds_read_b128 v[150:153], v133
	ds_read_b128 v[154:157], v133 offset:1024
	ds_read_b128 v[158:161], v133 offset:2048
	ds_read_b128 v[162:165], v133 offset:3072
	s_mov_b32 m0, s34
	ds_read_b128 v[166:169], v131 offset:32768
	ds_read_b128 v[170:173], v131 offset:33792
	ds_read_b128 v[174:177], v131 offset:34816
	ds_read_b128 v[178:181], v131 offset:35840
	ds_read_b128 v[182:185], v131 offset:36864
	ds_read_b128 v[186:189], v131 offset:37888
	ds_read_b128 v[202:205], v131 offset:38912
	ds_read_b128 v[206:209], v131 offset:39936
	global_load_lds_dwordx4 v128, s[52:53]
	s_mov_b32 m0, s35
	s_nop 0
	global_load_lds_dwordx4 v130, s[52:53]
	s_waitcnt vmcnt(8)
	s_waitcnt lgkmcnt(0)
	s_barrier
	s_setprio 1
	s_waitcnt lgkmcnt(0)
	v_mfma_f32_16x16x32_bf16 v[124:127], v[134:137], v[166:169], v[124:127]
	v_mfma_f32_16x16x32_bf16 v[120:123], v[142:145], v[166:169], v[120:123]
	v_mfma_f32_16x16x32_bf16 v[108:111], v[134:137], v[174:177], v[108:111]
	v_mfma_f32_16x16x32_bf16 v[104:107], v[142:145], v[174:177], v[104:107]
	v_mfma_f32_16x16x32_bf16 v[92:95], v[134:137], v[182:185], v[92:95]
	v_mfma_f32_16x16x32_bf16 v[88:91], v[142:145], v[182:185], v[88:91]
	v_mfma_f32_16x16x32_bf16 v[76:79], v[134:137], v[202:205], v[76:79]
	v_mfma_f32_16x16x32_bf16 v[72:75], v[142:145], v[202:205], v[72:75]
	v_mfma_f32_16x16x32_bf16 v[124:127], v[138:141], v[170:173], v[124:127]
	v_mfma_f32_16x16x32_bf16 v[120:123], v[146:149], v[170:173], v[120:123]
	v_mfma_f32_16x16x32_bf16 v[108:111], v[138:141], v[178:181], v[108:111]
	v_mfma_f32_16x16x32_bf16 v[104:107], v[146:149], v[178:181], v[104:107]
	v_mfma_f32_16x16x32_bf16 v[92:95], v[138:141], v[186:189], v[92:95]
	v_mfma_f32_16x16x32_bf16 v[88:91], v[146:149], v[186:189], v[88:91]
	v_mfma_f32_16x16x32_bf16 v[76:79], v[138:141], v[206:209], v[76:79]
	v_mfma_f32_16x16x32_bf16 v[72:75], v[146:149], v[206:209], v[72:75]
	s_setprio 0
	s_setprio 1
	v_mfma_f32_16x16x32_bf16 v[116:119], v[150:153], v[166:169], v[116:119]
	v_mfma_f32_16x16x32_bf16 v[112:115], v[158:161], v[166:169], v[112:115]
	v_mfma_f32_16x16x32_bf16 v[100:103], v[150:153], v[174:177], v[100:103]
	v_mfma_f32_16x16x32_bf16 v[96:99], v[158:161], v[174:177], v[96:99]
	v_mfma_f32_16x16x32_bf16 v[84:87], v[150:153], v[182:185], v[84:87]
	v_mfma_f32_16x16x32_bf16 v[80:83], v[158:161], v[182:185], v[80:83]
	v_mfma_f32_16x16x32_bf16 v[68:71], v[150:153], v[202:205], v[68:71]
	v_mfma_f32_16x16x32_bf16 v[64:67], v[158:161], v[202:205], v[64:67]
	v_mfma_f32_16x16x32_bf16 v[116:119], v[154:157], v[170:173], v[116:119]
	v_mfma_f32_16x16x32_bf16 v[112:115], v[162:165], v[170:173], v[112:115]
	v_mfma_f32_16x16x32_bf16 v[100:103], v[154:157], v[178:181], v[100:103]
	v_mfma_f32_16x16x32_bf16 v[96:99], v[162:165], v[178:181], v[96:99]
	v_mfma_f32_16x16x32_bf16 v[84:87], v[154:157], v[186:189], v[84:87]
	v_mfma_f32_16x16x32_bf16 v[80:83], v[162:165], v[186:189], v[80:83]
	v_mfma_f32_16x16x32_bf16 v[68:71], v[154:157], v[206:209], v[68:71]
	v_mfma_f32_16x16x32_bf16 v[64:67], v[162:165], v[206:209], v[64:67]
	s_setprio 0
	s_barrier
;     __device__ __forceinline__ const char* a(const Unit& u) const { return (const char*)A + (size_t)u.pm * 2 * hA(); }
;     __device__ __forceinline__ const char* b(const Unit& u) const { return (const char*)Bt + (size_t)u.pn * 2 * hB() + (size_t)(u.pm >> gshift) * goff; }
;     __device__ __forceinline__ const char* a(const Unit& u) const { return (const char*)A + (size_t)u.pm * 2 * hA(); }
;     __device__ __forceinline__ const char* b(const Unit& u) const { return (const char*)Bt + (size_t)((u.pn >> 4) * 4096 + (u.pn & 15) * 16) * 1024 * 2 + (size_t)(u.pm >> 1) * 512; }
;     __device__ __forceinline__ const char* a(const Unit&) const { return (const char*)A; }
;     __device__ __forceinline__ const char* b(const Unit& u) const { return (const char*)Bt + ((size_t)(((u.pm >> 4) * 1024 + u.pn * 256) * 16 + (u.pm & 15)) * 512) * 2; }
;     __device__ __forceinline__ void operator()(const f32x4 (&acc)[2][2][4][2], const Unit& u, int wr, int wc, int fr, int fq) const {
;     ...
;         for (int ai = 0; ai < 2; ++ai)
; #pragma unroll
;             for (int m = 0; m < 4; ++m) { const int r = row0 + ai * HALF + m * 16;
;                 bf16_t* rowp = hm ? base + ((size_t)((r >> 12) * 8 + (colt >> 7)) * 4096 + (r & 4095)) * 128 + wc * 32 + 8 * fq : base + (size_t)r * ldc + col0;
;                 float rv = sc; if (RS == 1) rv *= rsv[ai][m]; if (RS == 2) rv *= __builtin_amdgcn_rsqf(rsv[ai][m] * (1.0f / DM) + EPS);
; #pragma unroll
;                 for (int bj = 0; bj < 2; ++bj) { f32x4 v0 = acc[ai][bj][m][0] * rv, v1 = acc[ai][bj][m][1] * rv;
;                     if (CS) { v0 = v0 * cv[bj][0]; v1 = v1 * cv[bj][1]; }
;                     if (ACT == 2) {
; #pragma unroll
;                         for (int e = 0; e < 4; ++e) { float a = v0[e] > 0.f ? v0[e] : 0.f, b = v1[e] > 0.f ? v1[e] : 0.f; v0[e] = a * a; v1[e] = b * b; } }
;                     if (k8) {
;                         u32x2 w8; w8.x = pk_fp8x4(v0); w8.y = pk_fp8x4(v1);
;                         *(u32x2*)((unsigned char*)base + ((size_t)((r >> 12) * 8 + (colt >> 7) + bj) * 4096 + (r & 4095)) * 128 + wc * 32 + 8 * fq) = w8;
;                     } else {
;                     u32x4 w; w.x = cvt_pk_bf16(v0[0], v0[1]); w.y = cvt_pk_bf16(v0[2], v0[3]); w.z = cvt_pk_bf16(v1[0], v1[1]); w.w = cvt_pk_bf16(v1[2], v1[3]);
;                     *(u32x4*)(rowp + bj * bstep) = w; } } }
	s_add_i32 s22, s22, s33
	s_mov_b32 m0, s22
	ds_read_b128 v[166:169], v131 offset:49152
	ds_read_b128 v[170:173], v131 offset:50176
	ds_read_b128 v[174:177], v131 offset:51200
	ds_read_b128 v[178:181], v131 offset:52224
	ds_read_b128 v[182:185], v131 offset:53248
	ds_read_b128 v[186:189], v131 offset:54272
	ds_read_b128 v[202:205], v131 offset:55296
	ds_read_b128 v[206:209], v131 offset:56320
	global_load_lds_dwordx4 v192, s[66:67]
	s_add_i32 m0, s22, 0x2000
	s_add_i32 s22, s23, s33
	global_load_lds_dwordx4 v132, s[66:67]
	s_mov_b32 m0, s22
	s_nop 0
	global_load_lds_dwordx4 v192, s[46:47]
	s_add_i32 m0, s22, 0x2000
	s_nop 0
	global_load_lds_dwordx4 v132, s[46:47]
	s_mov_b32 m0, s54
	s_nop 0
	global_load_lds_dwordx4 v128, s[26:27]
	s_mov_b32 m0, s55
	s_nop 0
	global_load_lds_dwordx4 v130, s[26:27]
	v_fmamk_f32 v248, v240, 0x3a000000, v227
	v_rsq_f32_e32 v248, v248
	s_nop 0
	v_pk_mul_f32 v[120:121], v[120:121], v[248:249] op_sel_hi:[1,0]
	v_pk_mul_f32 v[122:123], v[122:123], v[248:249] op_sel_hi:[1,0]
	v_pk_mul_f32 v[124:125], v[124:125], v[248:249] op_sel_hi:[1,0]
	v_pk_mul_f32 v[126:127], v[126:127], v[248:249] op_sel_hi:[1,0]
	v_max_f32_e32 v120, 0, v120
	v_max_f32_e32 v121, 0, v121
	v_max_f32_e32 v122, 0, v122
	v_max_f32_e32 v123, 0, v123
	v_max_f32_e32 v124, 0, v124
	v_max_f32_e32 v125, 0, v125
	v_max_f32_e32 v126, 0, v126
	v_max_f32_e32 v127, 0, v127
	v_pk_mul_f32 v[120:121], v[120:121], v[120:121]
	v_pk_mul_f32 v[122:123], v[122:123], v[122:123]
	v_pk_mul_f32 v[124:125], v[124:125], v[124:125]
	v_pk_mul_f32 v[126:127], v[126:127], v[126:127]
	v_cvt_pk_bf16_f32 v124, v124, v125
	v_cvt_pk_bf16_f32 v125, v126, v127
	v_cvt_pk_bf16_f32 v126, v120, v121
	v_cvt_pk_bf16_f32 v127, v122, v123
	global_store_dwordx4 v250, v[124:127], s[98:99] sc1
	v_pk_mul_f32 v[112:113], v[112:113], v[248:249] op_sel_hi:[1,0]
	v_pk_mul_f32 v[114:115], v[114:115], v[248:249] op_sel_hi:[1,0]
	v_pk_mul_f32 v[116:117], v[116:117], v[248:249] op_sel_hi:[1,0]
	v_pk_mul_f32 v[118:119], v[118:119], v[248:249] op_sel_hi:[1,0]
	v_max_f32_e32 v112, 0, v112
	v_max_f32_e32 v113, 0, v113
	v_max_f32_e32 v114, 0, v114
	v_max_f32_e32 v115, 0, v115
	v_max_f32_e32 v116, 0, v116
	v_max_f32_e32 v117, 0, v117
	v_max_f32_e32 v118, 0, v118
	v_max_f32_e32 v119, 0, v119
	v_pk_mul_f32 v[112:113], v[112:113], v[112:113]
	v_pk_mul_f32 v[114:115], v[114:115], v[114:115]
	v_pk_mul_f32 v[116:117], v[116:117], v[116:117]
	v_pk_mul_f32 v[118:119], v[118:119], v[118:119]
	v_cvt_pk_bf16_f32 v116, v116, v117
	v_cvt_pk_bf16_f32 v117, v118, v119
	v_cvt_pk_bf16_f32 v118, v112, v113
	v_cvt_pk_bf16_f32 v119, v114, v115
	global_store_dwordx4 v250, v[116:119], s[98:99] offset:256 sc1
	s_add_u32 s98, s98, 0x40000
	s_addc_u32 s99, s99, 0
	v_fmamk_f32 v248, v241, 0x3a000000, v227
	v_rsq_f32_e32 v248, v248
	s_nop 0
	v_pk_mul_f32 v[104:105], v[104:105], v[248:249] op_sel_hi:[1,0]
	v_pk_mul_f32 v[106:107], v[106:107], v[248:249] op_sel_hi:[1,0]
	v_pk_mul_f32 v[108:109], v[108:109], v[248:249] op_sel_hi:[1,0]
	v_pk_mul_f32 v[110:111], v[110:111], v[248:249] op_sel_hi:[1,0]
	v_max_f32_e32 v104, 0, v104
	v_max_f32_e32 v105, 0, v105
	v_max_f32_e32 v106, 0, v106
	v_max_f32_e32 v107, 0, v107
	v_max_f32_e32 v108, 0, v108
	v_max_f32_e32 v109, 0, v109
	v_max_f32_e32 v110, 0, v110
	v_max_f32_e32 v111, 0, v111
	v_pk_mul_f32 v[104:105], v[104:105], v[104:105]
	v_pk_mul_f32 v[106:107], v[106:107], v[106:107]
	v_pk_mul_f32 v[108:109], v[108:109], v[108:109]
	v_pk_mul_f32 v[110:111], v[110:111], v[110:111]
	v_cvt_pk_bf16_f32 v108, v108, v109
	v_cvt_pk_bf16_f32 v109, v110, v111
	v_cvt_pk_bf16_f32 v110, v104, v105
	v_cvt_pk_bf16_f32 v111, v106, v107
	global_store_dwordx4 v250, v[108:111], s[98:99] sc1
	v_pk_mul_f32 v[96:97], v[96:97], v[248:249] op_sel_hi:[1,0]
	v_pk_mul_f32 v[98:99], v[98:99], v[248:249] op_sel_hi:[1,0]
	v_pk_mul_f32 v[100:101], v[100:101], v[248:249] op_sel_hi:[1,0]
	v_pk_mul_f32 v[102:103], v[102:103], v[248:249] op_sel_hi:[1,0]
	v_max_f32_e32 v96, 0, v96
	v_max_f32_e32 v97, 0, v97
	v_max_f32_e32 v98, 0, v98
	v_max_f32_e32 v99, 0, v99
	v_max_f32_e32 v100, 0, v100
	v_max_f32_e32 v101, 0, v101
	v_max_f32_e32 v102, 0, v102
	v_max_f32_e32 v103, 0, v103
	v_pk_mul_f32 v[96:97], v[96:97], v[96:97]
	v_pk_mul_f32 v[98:99], v[98:99], v[98:99]
	v_pk_mul_f32 v[100:101], v[100:101], v[100:101]
	v_pk_mul_f32 v[102:103], v[102:103], v[102:103]
	v_cvt_pk_bf16_f32 v100, v100, v101
	v_cvt_pk_bf16_f32 v101, v102, v103
	v_cvt_pk_bf16_f32 v102, v96, v97
	v_cvt_pk_bf16_f32 v103, v98, v99
	global_store_dwordx4 v250, v[100:103], s[98:99] offset:256 sc1
	s_add_u32 s98, s98, 0x40000
	s_addc_u32 s99, s99, 0
	s_waitcnt vmcnt(12)
	s_waitcnt lgkmcnt(0)
	s_barrier
;     __device__ __forceinline__ const char* a(const Unit& u) const { return (const char*)A + (size_t)u.pm * 2 * hA(); }
;     __device__ __forceinline__ const char* b(const Unit& u) const { return (const char*)Bt + (size_t)u.pn * 2 * hB() + (size_t)(u.pm >> gshift) * goff; }
;     __device__ __forceinline__ const char* a(const Unit& u) const { return (const char*)A + (size_t)u.pm * 2 * hA(); }
;     __device__ __forceinline__ const char* b(const Unit& u) const { return (const char*)Bt + (size_t)((u.pn >> 4) * 4096 + (u.pn & 15) * 16) * 1024 * 2 + (size_t)(u.pm >> 1) * 512; }
;     __device__ __forceinline__ const char* a(const Unit&) const { return (const char*)A; }
;     __device__ __forceinline__ const char* b(const Unit& u) const { return (const char*)Bt + ((size_t)(((u.pm >> 4) * 1024 + u.pn * 256) * 16 + (u.pm & 15)) * 512) * 2; }
;     __device__ __forceinline__ void operator()(const f32x4 (&acc)[2][2][4][2], const Unit& u, int wr, int wc, int fr, int fq) const {
;     ...
;         for (int ai = 0; ai < 2; ++ai)
; #pragma unroll
;             for (int m = 0; m < 4; ++m) { const int r = row0 + ai * HALF + m * 16;
;                 bf16_t* rowp = hm ? base + ((size_t)((r >> 12) * 8 + (colt >> 7)) * 4096 + (r & 4095)) * 128 + wc * 32 + 8 * fq : base + (size_t)r * ldc + col0;
;                 float rv = sc; if (RS == 1) rv *= rsv[ai][m]; if (RS == 2) rv *= __builtin_amdgcn_rsqf(rsv[ai][m] * (1.0f / DM) + EPS);
; #pragma unroll
;                 for (int bj = 0; bj < 2; ++bj) { f32x4 v0 = acc[ai][bj][m][0] * rv, v1 = acc[ai][bj][m][1] * rv;
;                     if (CS) { v0 = v0 * cv[bj][0]; v1 = v1 * cv[bj][1]; }
;                     if (ACT == 2) {
; #pragma unroll
;                         for (int e = 0; e < 4; ++e) { float a = v0[e] > 0.f ? v0[e] : 0.f, b = v1[e] > 0.f ? v1[e] : 0.f; v0[e] = a * a; v1[e] = b * b; } }
;                     if (k8) {
;                         u32x2 w8; w8.x = pk_fp8x4(v0); w8.y = pk_fp8x4(v1);
;                         *(u32x2*)((unsigned char*)base + ((size_t)((r >> 12) * 8 + (colt >> 7) + bj) * 4096 + (r & 4095)) * 128 + wc * 32 + 8 * fq) = w8;
;                     } else {
;                     u32x4 w; w.x = cvt_pk_bf16(v0[0], v0[1]); w.y = cvt_pk_bf16(v0[2], v0[3]); w.z = cvt_pk_bf16(v1[0], v1[1]); w.w = cvt_pk_bf16(v1[2], v1[3]);
;                     *(u32x4*)(rowp + bj * bstep) = w; } } }
	s_setprio 1
	s_waitcnt lgkmcnt(0)
	v_mfma_f32_16x16x32_bf16 v[60:63], v[134:137], v[166:169], v[60:63]
	v_fmamk_f32 v248, v242, 0x3a000000, v227
	v_rsq_f32_e32 v248, v248
	s_nop 0
	v_mfma_f32_16x16x32_bf16 v[56:59], v[142:145], v[166:169], v[56:59]
	v_pk_mul_f32 v[88:89], v[88:89], v[248:249] op_sel_hi:[1,0]
	v_pk_mul_f32 v[90:91], v[90:91], v[248:249] op_sel_hi:[1,0]
	v_pk_mul_f32 v[92:93], v[92:93], v[248:249] op_sel_hi:[1,0]
	v_mfma_f32_16x16x32_bf16 v[44:47], v[134:137], v[174:177], v[44:47]
	v_pk_mul_f32 v[94:95], v[94:95], v[248:249] op_sel_hi:[1,0]
	v_max_f32_e32 v88, 0, v88
	v_max_f32_e32 v89, 0, v89
	v_mfma_f32_16x16x32_bf16 v[40:43], v[142:145], v[174:177], v[40:43]
	v_max_f32_e32 v90, 0, v90
	v_max_f32_e32 v91, 0, v91
	v_max_f32_e32 v92, 0, v92
	v_mfma_f32_16x16x32_bf16 v[28:31], v[134:137], v[182:185], v[28:31]
	v_max_f32_e32 v93, 0, v93
	v_max_f32_e32 v94, 0, v94
	v_max_f32_e32 v95, 0, v95
	v_mfma_f32_16x16x32_bf16 v[24:27], v[142:145], v[182:185], v[24:27]
	v_pk_mul_f32 v[88:89], v[88:89], v[88:89]
	v_pk_mul_f32 v[90:91], v[90:91], v[90:91]
	v_pk_mul_f32 v[92:93], v[92:93], v[92:93]
	v_mfma_f32_16x16x32_bf16 v[12:15], v[134:137], v[202:205], v[12:15]
	v_pk_mul_f32 v[94:95], v[94:95], v[94:95]
	v_cvt_pk_bf16_f32 v92, v92, v93
	v_cvt_pk_bf16_f32 v93, v94, v95
	v_mfma_f32_16x16x32_bf16 v[8:11], v[142:145], v[202:205], v[8:11]
	v_cvt_pk_bf16_f32 v94, v88, v89
	v_cvt_pk_bf16_f32 v95, v90, v91
	global_store_dwordx4 v250, v[92:95], s[98:99] sc1
	v_mfma_f32_16x16x32_bf16 v[60:63], v[138:141], v[170:173], v[60:63]
	v_pk_mul_f32 v[80:81], v[80:81], v[248:249] op_sel_hi:[1,0]
	v_pk_mul_f32 v[82:83], v[82:83], v[248:249] op_sel_hi:[1,0]
	v_pk_mul_f32 v[84:85], v[84:85], v[248:249] op_sel_hi:[1,0]
	v_mfma_f32_16x16x32_bf16 v[56:59], v[146:149], v[170:173], v[56:59]
	v_pk_mul_f32 v[86:87], v[86:87], v[248:249] op_sel_hi:[1,0]
	v_max_f32_e32 v80, 0, v80
	v_max_f32_e32 v81, 0, v81
	v_mfma_f32_16x16x32_bf16 v[44:47], v[138:141], v[178:181], v[44:47]
	v_max_f32_e32 v82, 0, v82
	v_max_f32_e32 v83, 0, v83
	v_max_f32_e32 v84, 0, v84
	v_mfma_f32_16x16x32_bf16 v[40:43], v[146:149], v[178:181], v[40:43]
	v_max_f32_e32 v85, 0, v85
	v_max_f32_e32 v86, 0, v86
	v_max_f32_e32 v87, 0, v87
	v_mfma_f32_16x16x32_bf16 v[28:31], v[138:141], v[186:189], v[28:31]
	v_pk_mul_f32 v[80:81], v[80:81], v[80:81]
	v_pk_mul_f32 v[82:83], v[82:83], v[82:83]
	v_pk_mul_f32 v[84:85], v[84:85], v[84:85]
	v_mfma_f32_16x16x32_bf16 v[24:27], v[146:149], v[186:189], v[24:27]
	v_pk_mul_f32 v[86:87], v[86:87], v[86:87]
	v_cvt_pk_bf16_f32 v84, v84, v85
	v_cvt_pk_bf16_f32 v85, v86, v87
	v_mfma_f32_16x16x32_bf16 v[12:15], v[138:141], v[206:209], v[12:15]
	v_cvt_pk_bf16_f32 v86, v80, v81
	v_cvt_pk_bf16_f32 v87, v82, v83
	global_store_dwordx4 v250, v[84:87], s[98:99] offset:256 sc1
	v_mfma_f32_16x16x32_bf16 v[8:11], v[146:149], v[206:209], v[8:11]
	s_add_u32 s98, s98, 0x40000
	s_addc_u32 s99, s99, 0
	v_fmamk_f32 v248, v243, 0x3a000000, v227
	s_setprio 0
	s_setprio 1
	v_mfma_f32_16x16x32_bf16 v[52:55], v[150:153], v[166:169], v[52:55]
	v_rsq_f32_e32 v248, v248
	s_nop 0
	v_pk_mul_f32 v[72:73], v[72:73], v[248:249] op_sel_hi:[1,0]
	v_mfma_f32_16x16x32_bf16 v[48:51], v[158:161], v[166:169], v[48:51]
	v_pk_mul_f32 v[74:75], v[74:75], v[248:249] op_sel_hi:[1,0]
	v_pk_mul_f32 v[76:77], v[76:77], v[248:249] op_sel_hi:[1,0]
	v_pk_mul_f32 v[78:79], v[78:79], v[248:249] op_sel_hi:[1,0]
	v_mfma_f32_16x16x32_bf16 v[36:39], v[150:153], v[174:177], v[36:39]
	v_max_f32_e32 v72, 0, v72
	v_max_f32_e32 v73, 0, v73
	v_max_f32_e32 v74, 0, v74
	v_mfma_f32_16x16x32_bf16 v[32:35], v[158:161], v[174:177], v[32:35]
	v_max_f32_e32 v75, 0, v75
	v_max_f32_e32 v76, 0, v76
	v_max_f32_e32 v77, 0, v77
	v_mfma_f32_16x16x32_bf16 v[20:23], v[150:153], v[182:185], v[20:23]
	v_max_f32_e32 v78, 0, v78
	v_max_f32_e32 v79, 0, v79
	v_pk_mul_f32 v[72:73], v[72:73], v[72:73]
	v_mfma_f32_16x16x32_bf16 v[16:19], v[158:161], v[182:185], v[16:19]
	v_pk_mul_f32 v[74:75], v[74:75], v[74:75]
	v_pk_mul_f32 v[76:77], v[76:77], v[76:77]
	v_pk_mul_f32 v[78:79], v[78:79], v[78:79]
	v_mfma_f32_16x16x32_bf16 v[4:7], v[150:153], v[202:205], v[4:7]
	v_cvt_pk_bf16_f32 v76, v76, v77
	v_cvt_pk_bf16_f32 v77, v78, v79
	v_cvt_pk_bf16_f32 v78, v72, v73
	v_mfma_f32_16x16x32_bf16 v[0:3], v[158:161], v[202:205], v[0:3]
	v_cvt_pk_bf16_f32 v79, v74, v75
	global_store_dwordx4 v250, v[76:79], s[98:99] sc1
	v_pk_mul_f32 v[64:65], v[64:65], v[248:249] op_sel_hi:[1,0]
	v_mfma_f32_16x16x32_bf16 v[52:55], v[154:157], v[170:173], v[52:55]
	v_pk_mul_f32 v[66:67], v[66:67], v[248:249] op_sel_hi:[1,0]
	v_pk_mul_f32 v[68:69], v[68:69], v[248:249] op_sel_hi:[1,0]
	v_pk_mul_f32 v[70:71], v[70:71], v[248:249] op_sel_hi:[1,0]
	v_mfma_f32_16x16x32_bf16 v[48:51], v[162:165], v[170:173], v[48:51]
	v_max_f32_e32 v64, 0, v64
	v_max_f32_e32 v65, 0, v65
	v_max_f32_e32 v66, 0, v66
	v_mfma_f32_16x16x32_bf16 v[36:39], v[154:157], v[178:181], v[36:39]
	v_max_f32_e32 v67, 0, v67
	v_max_f32_e32 v68, 0, v68
	v_max_f32_e32 v69, 0, v69
	v_mfma_f32_16x16x32_bf16 v[32:35], v[162:165], v[178:181], v[32:35]
	v_max_f32_e32 v70, 0, v70
	v_max_f32_e32 v71, 0, v71
	v_pk_mul_f32 v[64:65], v[64:65], v[64:65]
	v_mfma_f32_16x16x32_bf16 v[20:23], v[154:157], v[186:189], v[20:23]
	v_pk_mul_f32 v[66:67], v[66:67], v[66:67]
	v_pk_mul_f32 v[68:69], v[68:69], v[68:69]
	v_pk_mul_f32 v[70:71], v[70:71], v[70:71]
	v_mfma_f32_16x16x32_bf16 v[16:19], v[162:165], v[186:189], v[16:19]
	v_cvt_pk_bf16_f32 v68, v68, v69
	v_cvt_pk_bf16_f32 v69, v70, v71
	v_cvt_pk_bf16_f32 v70, v64, v65
	v_mfma_f32_16x16x32_bf16 v[4:7], v[154:157], v[206:209], v[4:7]
	v_cvt_pk_bf16_f32 v71, v66, v67
	global_store_dwordx4 v250, v[68:71], s[98:99] offset:256 sc1
	s_add_u32 s98, s98, 0x40000
	v_mfma_f32_16x16x32_bf16 v[0:3], v[162:165], v[206:209], v[0:3]
	s_addc_u32 s99, s99, 0
	s_setprio 0
	s_barrier
;     __device__ __forceinline__ const char* a(const Unit& u) const { return (const char*)A + (size_t)u.pm * 2 * hA(); }
;     __device__ __forceinline__ const char* b(const Unit& u) const { return (const char*)Bt + (size_t)u.pn * 2 * hB() + (size_t)(u.pm >> gshift) * goff; }
;     __device__ __forceinline__ const char* a(const Unit& u) const { return (const char*)A + (size_t)u.pm * 2 * hA(); }
;     __device__ __forceinline__ const char* b(const Unit& u) const { return (const char*)Bt + (size_t)((u.pn >> 4) * 4096 + (u.pn & 15) * 16) * 1024 * 2 + (size_t)(u.pm >> 1) * 512; }
;     __device__ __forceinline__ const char* a(const Unit&) const { return (const char*)A; }
;     __device__ __forceinline__ const char* b(const Unit& u) const { return (const char*)Bt + ((size_t)(((u.pm >> 4) * 1024 + u.pn * 256) * 16 + (u.pm & 15)) * 512) * 2; }
;     __device__ __forceinline__ void operator()(const f32x4 (&acc)[2][2][4][2], const Unit& u, int wr, int wc, int fr, int fq) const {
;     ...
;         for (int ai = 0; ai < 2; ++ai)
; #pragma unroll
;             for (int m = 0; m < 4; ++m) { const int r = row0 + ai * HALF + m * 16;
;                 bf16_t* rowp = hm ? base + ((size_t)((r >> 12) * 8 + (colt >> 7)) * 4096 + (r & 4095)) * 128 + wc * 32 + 8 * fq : base + (size_t)r * ldc + col0;
;                 float rv = sc; if (RS == 1) rv *= rsv[ai][m]; if (RS == 2) rv *= __builtin_amdgcn_rsqf(rsv[ai][m] * (1.0f / DM) + EPS);
; #pragma unroll
;                 for (int bj = 0; bj < 2; ++bj) { f32x4 v0 = acc[ai][bj][m][0] * rv, v1 = acc[ai][bj][m][1] * rv;
;                     if (CS) { v0 = v0 * cv[bj][0]; v1 = v1 * cv[bj][1]; }
;                     if (ACT == 2) {
; #pragma unroll
;                         for (int e = 0; e < 4; ++e) { float a = v0[e] > 0.f ? v0[e] : 0.f, b = v1[e] > 0.f ? v1[e] : 0.f; v0[e] = a * a; v1[e] = b * b; } }
;                     if (k8) {
;                         u32x2 w8; w8.x = pk_fp8x4(v0); w8.y = pk_fp8x4(v1);
;                         *(u32x2*)((unsigned char*)base + ((size_t)((r >> 12) * 8 + (colt >> 7) + bj) * 4096 + (r & 4095)) * 128 + wc * 32 + 8 * fq) = w8;
;                     } else {
;                     u32x4 w; w.x = cvt_pk_bf16(v0[0], v0[1]); w.y = cvt_pk_bf16(v0[2], v0[3]); w.z = cvt_pk_bf16(v1[0], v1[1]); w.w = cvt_pk_bf16(v1[2], v1[3]);
;                     *(u32x4*)(rowp + bj * bstep) = w; } } }
	s_nop 7
	v_fmamk_f32 v248, v244, 0x3a000000, v227
	v_rsq_f32_e32 v248, v248
	s_nop 0
	v_pk_mul_f32 v[56:57], v[56:57], v[248:249] op_sel_hi:[1,0]
	v_pk_mul_f32 v[58:59], v[58:59], v[248:249] op_sel_hi:[1,0]
	v_pk_mul_f32 v[60:61], v[60:61], v[248:249] op_sel_hi:[1,0]
	v_pk_mul_f32 v[62:63], v[62:63], v[248:249] op_sel_hi:[1,0]
	v_max_f32_e32 v56, 0, v56
	v_max_f32_e32 v57, 0, v57
	v_max_f32_e32 v58, 0, v58
	v_max_f32_e32 v59, 0, v59
	v_max_f32_e32 v60, 0, v60
	v_max_f32_e32 v61, 0, v61
	v_max_f32_e32 v62, 0, v62
	v_max_f32_e32 v63, 0, v63
	v_pk_mul_f32 v[56:57], v[56:57], v[56:57]
	v_pk_mul_f32 v[58:59], v[58:59], v[58:59]
	v_pk_mul_f32 v[60:61], v[60:61], v[60:61]
	v_pk_mul_f32 v[62:63], v[62:63], v[62:63]
	v_cvt_pk_bf16_f32 v60, v60, v61
	v_cvt_pk_bf16_f32 v61, v62, v63
	v_cvt_pk_bf16_f32 v62, v56, v57
	v_cvt_pk_bf16_f32 v63, v58, v59
	global_store_dwordx4 v250, v[60:63], s[100:101] sc1
	v_pk_mul_f32 v[48:49], v[48:49], v[248:249] op_sel_hi:[1,0]
	v_pk_mul_f32 v[50:51], v[50:51], v[248:249] op_sel_hi:[1,0]
	v_pk_mul_f32 v[52:53], v[52:53], v[248:249] op_sel_hi:[1,0]
	v_pk_mul_f32 v[54:55], v[54:55], v[248:249] op_sel_hi:[1,0]
	v_max_f32_e32 v48, 0, v48
	v_max_f32_e32 v49, 0, v49
	v_max_f32_e32 v50, 0, v50
	v_max_f32_e32 v51, 0, v51
	v_max_f32_e32 v52, 0, v52
	v_max_f32_e32 v53, 0, v53
	v_max_f32_e32 v54, 0, v54
	v_max_f32_e32 v55, 0, v55
	v_pk_mul_f32 v[48:49], v[48:49], v[48:49]
	v_pk_mul_f32 v[50:51], v[50:51], v[50:51]
	v_pk_mul_f32 v[52:53], v[52:53], v[52:53]
	v_pk_mul_f32 v[54:55], v[54:55], v[54:55]
	v_cvt_pk_bf16_f32 v52, v52, v53
	v_cvt_pk_bf16_f32 v53, v54, v55
	v_cvt_pk_bf16_f32 v54, v48, v49
	v_cvt_pk_bf16_f32 v55, v50, v51
	global_store_dwordx4 v250, v[52:55], s[100:101] offset:256 sc1
	s_add_u32 s100, s100, 0x40000
	s_addc_u32 s101, s101, 0
	v_fmamk_f32 v248, v245, 0x3a000000, v227
	v_rsq_f32_e32 v248, v248
	s_nop 0
	v_pk_mul_f32 v[40:41], v[40:41], v[248:249] op_sel_hi:[1,0]
	v_pk_mul_f32 v[42:43], v[42:43], v[248:249] op_sel_hi:[1,0]
	v_pk_mul_f32 v[44:45], v[44:45], v[248:249] op_sel_hi:[1,0]
	v_pk_mul_f32 v[46:47], v[46:47], v[248:249] op_sel_hi:[1,0]
	v_max_f32_e32 v40, 0, v40
	v_max_f32_e32 v41, 0, v41
	v_max_f32_e32 v42, 0, v42
	v_max_f32_e32 v43, 0, v43
	v_max_f32_e32 v44, 0, v44
	v_max_f32_e32 v45, 0, v45
	v_max_f32_e32 v46, 0, v46
	v_max_f32_e32 v47, 0, v47
	v_pk_mul_f32 v[40:41], v[40:41], v[40:41]
	v_pk_mul_f32 v[42:43], v[42:43], v[42:43]
	v_pk_mul_f32 v[44:45], v[44:45], v[44:45]
	v_pk_mul_f32 v[46:47], v[46:47], v[46:47]
	v_cvt_pk_bf16_f32 v44, v44, v45
	v_cvt_pk_bf16_f32 v45, v46, v47
	v_cvt_pk_bf16_f32 v46, v40, v41
	v_cvt_pk_bf16_f32 v47, v42, v43
	global_store_dwordx4 v250, v[44:47], s[100:101] sc1
	v_pk_mul_f32 v[32:33], v[32:33], v[248:249] op_sel_hi:[1,0]
	v_pk_mul_f32 v[34:35], v[34:35], v[248:249] op_sel_hi:[1,0]
	v_pk_mul_f32 v[36:37], v[36:37], v[248:249] op_sel_hi:[1,0]
	v_pk_mul_f32 v[38:39], v[38:39], v[248:249] op_sel_hi:[1,0]
	v_max_f32_e32 v32, 0, v32
	v_max_f32_e32 v33, 0, v33
	v_max_f32_e32 v34, 0, v34
	v_max_f32_e32 v35, 0, v35
	v_max_f32_e32 v36, 0, v36
	v_max_f32_e32 v37, 0, v37
	v_max_f32_e32 v38, 0, v38
	v_max_f32_e32 v39, 0, v39
	v_pk_mul_f32 v[32:33], v[32:33], v[32:33]
	v_pk_mul_f32 v[34:35], v[34:35], v[34:35]
	v_pk_mul_f32 v[36:37], v[36:37], v[36:37]
	v_pk_mul_f32 v[38:39], v[38:39], v[38:39]
	v_cvt_pk_bf16_f32 v36, v36, v37
	v_cvt_pk_bf16_f32 v37, v38, v39
	v_cvt_pk_bf16_f32 v38, v32, v33
	v_cvt_pk_bf16_f32 v39, v34, v35
	global_store_dwordx4 v250, v[36:39], s[100:101] offset:256 sc1
	s_add_u32 s100, s100, 0x40000
;     __device__ __forceinline__ const char* a(const Unit& u) const { return (const char*)A + (size_t)u.pm * 2 * hA(); }
;     __device__ __forceinline__ const char* b(const Unit& u) const { return (const char*)Bt + (size_t)u.pn * 2 * hB() + (size_t)(u.pm >> gshift) * goff; }
;     __device__ __forceinline__ const char* a(const Unit& u) const { return (const char*)A + (size_t)u.pm * 2 * hA(); }
;     __device__ __forceinline__ const char* b(const Unit& u) const { return (const char*)Bt + (size_t)((u.pn >> 4) * 4096 + (u.pn & 15) * 16) * 1024 * 2 + (size_t)(u.pm >> 1) * 512; }
;     __device__ __forceinline__ const char* a(const Unit&) const { return (const char*)A; }
; #define PG8_BAR __builtin_amdgcn_s_barrier()
;     __device__ __forceinline__ void operator()(const f32x4 (&acc)[2][2][4][2], const Unit& u, int wr, int wc, int fr, int fq) const {
;     ...
;         for (int ai = 0; ai < 2; ++ai)
; #pragma unroll
;             for (int m = 0; m < 4; ++m) { const int r = row0 + ai * HALF + m * 16;
;                 bf16_t* rowp = hm ? base + ((size_t)((r >> 12) * 8 + (colt >> 7)) * 4096 + (r & 4095)) * 128 + wc * 32 + 8 * fq : base + (size_t)r * ldc + col0;
;                 float rv = sc; if (RS == 1) rv *= rsv[ai][m]; if (RS == 2) rv *= __builtin_amdgcn_rsqf(rsv[ai][m] * (1.0f / DM) + EPS);
; #pragma unroll
;                 for (int bj = 0; bj < 2; ++bj) { f32x4 v0 = acc[ai][bj][m][0] * rv, v1 = acc[ai][bj][m][1] * rv;
;                     if (CS) { v0 = v0 * cv[bj][0]; v1 = v1 * cv[bj][1]; }
;                     if (ACT == 2) {
; #pragma unroll
;                         for (int e = 0; e < 4; ++e) { float a = v0[e] > 0.f ? v0[e] : 0.f, b = v1[e] > 0.f ? v1[e] : 0.f; v0[e] = a * a; v1[e] = b * b; } }
;                     if (k8) {
;                         u32x2 w8; w8.x = pk_fp8x4(v0); w8.y = pk_fp8x4(v1);
;                         *(u32x2*)((unsigned char*)base + ((size_t)((r >> 12) * 8 + (colt >> 7) + bj) * 4096 + (r & 4095)) * 128 + wc * 32 + 8 * fq) = w8;
;                     } else {
;                     u32x4 w; w.x = cvt_pk_bf16(v0[0], v0[1]); w.y = cvt_pk_bf16(v0[2], v0[3]); w.z = cvt_pk_bf16(v1[0], v1[1]); w.w = cvt_pk_bf16(v1[2], v1[3]);
;                     *(u32x4*)(rowp + bj * bstep) = w; } } }
;     ...
;         if constexpr (ALIGN_EPI) { if (wr == 0) PG8_BAR; }
;         E(acc, cur, wr, wc, 0, 0); S.done(cur);
;         if (!has_next) break;
	s_addc_u32 s101, s101, 0
	v_fmamk_f32 v248, v246, 0x3a000000, v227
	v_rsq_f32_e32 v248, v248
	s_nop 0
	v_pk_mul_f32 v[24:25], v[24:25], v[248:249] op_sel_hi:[1,0]
	v_pk_mul_f32 v[26:27], v[26:27], v[248:249] op_sel_hi:[1,0]
	v_pk_mul_f32 v[28:29], v[28:29], v[248:249] op_sel_hi:[1,0]
	v_pk_mul_f32 v[30:31], v[30:31], v[248:249] op_sel_hi:[1,0]
	v_max_f32_e32 v24, 0, v24
	v_max_f32_e32 v25, 0, v25
	v_max_f32_e32 v26, 0, v26
	v_max_f32_e32 v27, 0, v27
	v_max_f32_e32 v28, 0, v28
	v_max_f32_e32 v29, 0, v29
	v_max_f32_e32 v30, 0, v30
	v_max_f32_e32 v31, 0, v31
	v_pk_mul_f32 v[24:25], v[24:25], v[24:25]
	v_pk_mul_f32 v[26:27], v[26:27], v[26:27]
	v_pk_mul_f32 v[28:29], v[28:29], v[28:29]
	v_pk_mul_f32 v[30:31], v[30:31], v[30:31]
	v_cvt_pk_bf16_f32 v28, v28, v29
	v_cvt_pk_bf16_f32 v29, v30, v31
	v_cvt_pk_bf16_f32 v30, v24, v25
	v_cvt_pk_bf16_f32 v31, v26, v27
	global_store_dwordx4 v250, v[28:31], s[100:101] sc1
	v_pk_mul_f32 v[16:17], v[16:17], v[248:249] op_sel_hi:[1,0]
	v_pk_mul_f32 v[18:19], v[18:19], v[248:249] op_sel_hi:[1,0]
	v_pk_mul_f32 v[20:21], v[20:21], v[248:249] op_sel_hi:[1,0]
	v_pk_mul_f32 v[22:23], v[22:23], v[248:249] op_sel_hi:[1,0]
	v_max_f32_e32 v16, 0, v16
	v_max_f32_e32 v17, 0, v17
	v_max_f32_e32 v18, 0, v18
	v_max_f32_e32 v19, 0, v19
	v_max_f32_e32 v20, 0, v20
	v_max_f32_e32 v21, 0, v21
	v_max_f32_e32 v22, 0, v22
	v_max_f32_e32 v23, 0, v23
	v_pk_mul_f32 v[16:17], v[16:17], v[16:17]
	v_pk_mul_f32 v[18:19], v[18:19], v[18:19]
	v_pk_mul_f32 v[20:21], v[20:21], v[20:21]
	v_pk_mul_f32 v[22:23], v[22:23], v[22:23]
	v_cvt_pk_bf16_f32 v20, v20, v21
	v_cvt_pk_bf16_f32 v21, v22, v23
	v_cvt_pk_bf16_f32 v22, v16, v17
	v_cvt_pk_bf16_f32 v23, v18, v19
	global_store_dwordx4 v250, v[20:23], s[100:101] offset:256 sc1
	s_add_u32 s100, s100, 0x40000
	s_addc_u32 s101, s101, 0
	v_fmamk_f32 v248, v247, 0x3a000000, v227
	v_rsq_f32_e32 v248, v248
	s_nop 0
	v_pk_mul_f32 v[8:9], v[8:9], v[248:249] op_sel_hi:[1,0]
	v_pk_mul_f32 v[10:11], v[10:11], v[248:249] op_sel_hi:[1,0]
	v_pk_mul_f32 v[12:13], v[12:13], v[248:249] op_sel_hi:[1,0]
	v_pk_mul_f32 v[14:15], v[14:15], v[248:249] op_sel_hi:[1,0]
	v_max_f32_e32 v8, 0, v8
	v_max_f32_e32 v9, 0, v9
	v_max_f32_e32 v10, 0, v10
	v_max_f32_e32 v11, 0, v11
	v_max_f32_e32 v12, 0, v12
	v_max_f32_e32 v13, 0, v13
	v_max_f32_e32 v14, 0, v14
	v_max_f32_e32 v15, 0, v15
	v_pk_mul_f32 v[8:9], v[8:9], v[8:9]
	v_pk_mul_f32 v[10:11], v[10:11], v[10:11]
	v_pk_mul_f32 v[12:13], v[12:13], v[12:13]
	v_pk_mul_f32 v[14:15], v[14:15], v[14:15]
	v_cvt_pk_bf16_f32 v12, v12, v13
	v_cvt_pk_bf16_f32 v13, v14, v15
	v_cvt_pk_bf16_f32 v14, v8, v9
	v_cvt_pk_bf16_f32 v15, v10, v11
	global_store_dwordx4 v250, v[12:15], s[100:101] sc1
	v_pk_mul_f32 v[0:1], v[0:1], v[248:249] op_sel_hi:[1,0]
	v_pk_mul_f32 v[2:3], v[2:3], v[248:249] op_sel_hi:[1,0]
	v_pk_mul_f32 v[4:5], v[4:5], v[248:249] op_sel_hi:[1,0]
	v_pk_mul_f32 v[6:7], v[6:7], v[248:249] op_sel_hi:[1,0]
	v_max_f32_e32 v0, 0, v0
	v_max_f32_e32 v1, 0, v1
	v_max_f32_e32 v2, 0, v2
	v_max_f32_e32 v3, 0, v3
	v_max_f32_e32 v4, 0, v4
	v_max_f32_e32 v5, 0, v5
	v_max_f32_e32 v6, 0, v6
	v_max_f32_e32 v7, 0, v7
	v_pk_mul_f32 v[0:1], v[0:1], v[0:1]
	v_pk_mul_f32 v[2:3], v[2:3], v[2:3]
	v_pk_mul_f32 v[4:5], v[4:5], v[4:5]
	v_pk_mul_f32 v[6:7], v[6:7], v[6:7]
	v_cvt_pk_bf16_f32 v4, v4, v5
	v_cvt_pk_bf16_f32 v5, v6, v7
	v_cvt_pk_bf16_f32 v6, v0, v1
	v_cvt_pk_bf16_f32 v7, v2, v3
	global_store_dwordx4 v250, v[4:7], s[100:101] offset:256 sc1
	s_add_u32 s100, s100, 0x40000
	s_addc_u32 s101, s101, 0
	s_cmp_lg_u64 s[82:83], 0
	s_cbranch_scc0 mk_p5_fin_nobar
	s_barrier
